# UPCONV K-loop: LDS-DMA loads addressed by scalar base + 32-bit lane offset (no per-load 64-bit VALU adds)
# speedup vs baseline: 1.0102x; 1.0008x over previous
; #define PG8_STAGE(bufoff, gbase, voff) do { _Pragma("unroll") for (int _i = 0; _i < 2; ++_i) \
;         __builtin_amdgcn_global_load_lds((const unsigned*)((const char*)(gbase) + (voff)[_i]), (PG8_LAS unsigned*)(lds + (bufoff) + ldsw + _i * 8192), 16, 0, 0); } while (0)
; #define PG8_LDA(dst, b, h) do { _Pragma("unroll") for (int m = 0; m < 4; ++m) _Pragma("unroll") for (int k = 0; k < 2; ++k) dst[m][k] = *(const PG8_LAS bf16x8*)(lds + PG8_SA(b, h) + aoff + m * 2048 + k * 1024); } while (0)
; #define PG8_LDB(dst, b, h) do { _Pragma("unroll") for (int n = 0; n < 2; ++n) _Pragma("unroll") for (int k = 0; k < 2; ++k) dst[n][k] = *(const PG8_LAS bf16x8*)(lds + PG8_SB(b, h) + boff + n * 2048 + k * 1024); } while (0)
; #define PG8_MMA(ai, bj, At, Bt) do { __builtin_amdgcn_s_setprio(1); _Pragma("unroll") for (int m = 0; m < 4; ++m) _Pragma("unroll") for (int n = 0; n < 2; ++n) _Pragma("unroll") for (int k = 0; k < 2; ++k) \
;         acc[ai][bj][m][n] = __builtin_amdgcn_mfma_f32_16x16x32_bf16(Bt[n][k], At[m][k], acc[ai][bj][m][n], 0, 0, 0); __builtin_amdgcn_s_setprio(0); } while (0)
; #define PG8_WAIT_V(n) asm volatile("s_waitcnt vmcnt(" #n ")" ::: "memory")
; #define PG8_WAIT_L(n) asm volatile("s_waitcnt lgkmcnt(" #n ")" ::: "memory")
; template <class Epi, class Sched, bool ALIGN_EPI = false, bool SP2 = false>
; __device__ __forceinline__ void gemm_phase(PG8_LAS unsigned char* lds, const Gemm g, const Sched& S, const Epi& E, int wave_in) {
;     ...
;             const bool last = (t == nt - 2);
;             const char* a1 = cA + (size_t)(t + 1) * kstep;
;             const char* a2 = last ? nA : cA + (size_t)(t + 2) * kstep; const char* b2 = last ? nB : cB + (size_t)(t + 2) * kstep;
;             const char* a3 = a2 + kstep; const char* b3 = b2 + kstep;
;             if (last && has_next) S.a_ready(nxt);
;             if constexpr (SP2) {
;             PG8_LDB(B0, 0, 0); PG8_LDB(B1, 0, 1); PG8_SCHED; PG8_LDA(At, 0, 0); PG8_STAGE(PG8_SA(1, 1), a1 + hstepA, voffA);
;             PG8_WAIT_V(8); PG8_WAIT_L(0); PG8_BAR; PG8_MMA(0, 0, At, B0); PG8_MMA(0, 1, At, B1); PG8_BAR; PG8_SCHED;
;             PG8_LDA(At, 0, 1); PG8_STAGE(PG8_SB(0, 0), b2, voffB); PG8_STAGE(PG8_SB(0, 1), b2 + hstep, voffB); PG8_STAGE(PG8_SA(0, 0), a2, voffA);
;             PG8_WAIT_V(8); PG8_WAIT_L(0); PG8_BAR; PG8_MMA(1, 0, At, B0); PG8_MMA(1, 1, At, B1); PG8_BAR; PG8_SCHED;
.LBB0_43:
	s_add_u32 s50, s48, 0xfff80080
	s_addc_u32 s51, s49, -1
	s_add_i32 s72, 0, 0x10000
	s_cmp_eq_u32 s71, 28
	s_cselect_b32 s53, s43, s51
	s_cselect_b32 s52, s67, s50
	s_cselect_b32 s51, s41, s70
	s_cselect_b32 s50, s68, s69
	s_add_i32 s74, 0, 0x14000
	v_add_u32_e32 v118, s72, v214
	v_add_u32_e32 v178, s74, v214
	ds_read_b128 v[106:109], v118
	ds_read_b128 v[110:113], v118 offset:1024
	ds_read_b128 v[114:117], v118 offset:2048
	ds_read_b128 v[118:121], v118 offset:3072
	ds_read_b128 v[122:125], v178
	ds_read_b128 v[126:129], v178 offset:1024
	ds_read_b128 v[130:133], v178 offset:2048
	ds_read_b128 v[178:181], v178 offset:3072
	s_add_i32 m0, s58, 0xc000
	ds_read_b128 v[182:185], v217
	ds_read_b128 v[186:189], v217 offset:1024
	ds_read_b128 v[190:193], v217 offset:2048
	ds_read_b128 v[218:221], v217 offset:3072
	ds_read_b128 v[222:225], v217 offset:4096
	ds_read_b128 v[226:229], v217 offset:5120
	ds_read_b128 v[230:233], v217 offset:6144
	ds_read_b128 v[234:237], v217 offset:7168
	global_load_lds_dwordx4 v174, s[48:49]
	s_add_i32 m0, s58, 0xe000
	s_nop 0
	global_load_lds_dwordx4 v176, s[48:49]
	s_waitcnt vmcnt(8)
	s_waitcnt lgkmcnt(0)
	s_barrier
	s_waitcnt lgkmcnt(0)
	v_mfma_f32_16x16x32_bf16 v[154:157], v[106:109], v[182:185], v[154:157]
	v_mfma_f32_16x16x32_bf16 v[62:65], v[114:117], v[182:185], v[62:65]
	v_mfma_f32_16x16x32_bf16 v[150:153], v[106:109], v[190:193], v[150:153]
	v_mfma_f32_16x16x32_bf16 v[54:57], v[114:117], v[190:193], v[54:57]
	v_mfma_f32_16x16x32_bf16 v[142:145], v[106:109], v[222:225], v[142:145]
	v_mfma_f32_16x16x32_bf16 v[46:49], v[114:117], v[222:225], v[46:49]
	v_mfma_f32_16x16x32_bf16 v[102:105], v[106:109], v[230:233], v[102:105]
	v_mfma_f32_16x16x32_bf16 v[38:41], v[114:117], v[230:233], v[38:41]
	v_mfma_f32_16x16x32_bf16 v[154:157], v[110:113], v[186:189], v[154:157]
	v_mfma_f32_16x16x32_bf16 v[62:65], v[118:121], v[186:189], v[62:65]
	v_mfma_f32_16x16x32_bf16 v[150:153], v[110:113], v[218:221], v[150:153]
	v_mfma_f32_16x16x32_bf16 v[54:57], v[118:121], v[218:221], v[54:57]
	v_mfma_f32_16x16x32_bf16 v[142:145], v[110:113], v[226:229], v[142:145]
	v_mfma_f32_16x16x32_bf16 v[46:49], v[118:121], v[226:229], v[46:49]
	v_mfma_f32_16x16x32_bf16 v[102:105], v[110:113], v[234:237], v[102:105]
	v_mfma_f32_16x16x32_bf16 v[38:41], v[118:121], v[234:237], v[38:41]
	v_mfma_f32_16x16x32_bf16 v[134:137], v[122:125], v[182:185], v[134:137]
	v_mfma_f32_16x16x32_bf16 v[58:61], v[130:133], v[182:185], v[58:61]
	v_mfma_f32_16x16x32_bf16 v[146:149], v[122:125], v[190:193], v[146:149]
	v_mfma_f32_16x16x32_bf16 v[50:53], v[130:133], v[190:193], v[50:53]
	v_mfma_f32_16x16x32_bf16 v[138:141], v[122:125], v[222:225], v[138:141]
	v_mfma_f32_16x16x32_bf16 v[42:45], v[130:133], v[222:225], v[42:45]
	v_mfma_f32_16x16x32_bf16 v[98:101], v[122:125], v[230:233], v[98:101]
	v_mfma_f32_16x16x32_bf16 v[34:37], v[130:133], v[230:233], v[34:37]
	v_mfma_f32_16x16x32_bf16 v[134:137], v[126:129], v[186:189], v[134:137]
	v_mfma_f32_16x16x32_bf16 v[58:61], v[178:181], v[186:189], v[58:61]
	v_mfma_f32_16x16x32_bf16 v[146:149], v[126:129], v[218:221], v[146:149]
	v_mfma_f32_16x16x32_bf16 v[50:53], v[178:181], v[218:221], v[50:53]
	v_mfma_f32_16x16x32_bf16 v[138:141], v[126:129], v[226:229], v[138:141]
	v_mfma_f32_16x16x32_bf16 v[42:45], v[178:181], v[226:229], v[42:45]
	v_mfma_f32_16x16x32_bf16 v[98:101], v[126:129], v[234:237], v[98:101]
	v_mfma_f32_16x16x32_bf16 v[34:37], v[178:181], v[234:237], v[34:37]
	s_barrier
	s_add_i32 s72, s72, s57
	s_add_u32 vcc_lo, s50, s84
	s_addc_u32 vcc_hi, s51, s85
	s_mov_b32 m0, s72
	ds_read_b128 v[182:185], v217 offset:16384
	ds_read_b128 v[186:189], v217 offset:17408
	ds_read_b128 v[190:193], v217 offset:18432
	ds_read_b128 v[218:221], v217 offset:19456
	ds_read_b128 v[222:225], v217 offset:20480
	ds_read_b128 v[226:229], v217 offset:21504
	ds_read_b128 v[230:233], v217 offset:22528
	ds_read_b128 v[234:237], v217 offset:23552
	global_load_lds_dwordx4 v0, s[50:51]
	s_add_i32 m0, s72, 0x2000
	s_add_u32 s72, s50, 0x80000
	s_addc_u32 s73, s51, 0
	s_add_i32 s74, s74, s57
	global_load_lds_dwordx4 v168, s[50:51]
	s_mov_b32 m0, s74
	s_add_u32 s98, s52, s84
	s_addc_u32 s99, s53, s85
	global_load_lds_dwordx4 v0, s[72:73]
	s_add_i32 m0, s74, 0x2000
	s_nop 0
	global_load_lds_dwordx4 v168, s[72:73]
	s_mov_b32 m0, s58
	s_nop 0
	global_load_lds_dwordx4 v172, s[52:53]
	s_mov_b32 m0, s59
	s_nop 0
	global_load_lds_dwordx4 v170, s[52:53]
	s_waitcnt vmcnt(8)
	s_waitcnt lgkmcnt(0)
	s_barrier
	s_waitcnt lgkmcnt(0)
	v_mfma_f32_16x16x32_bf16 v[94:97], v[106:109], v[182:185], v[94:97]
	v_mfma_f32_16x16x32_bf16 v[30:33], v[114:117], v[182:185], v[30:33]
	v_mfma_f32_16x16x32_bf16 v[86:89], v[106:109], v[190:193], v[86:89]
	v_mfma_f32_16x16x32_bf16 v[22:25], v[114:117], v[190:193], v[22:25]
	v_mfma_f32_16x16x32_bf16 v[78:81], v[106:109], v[222:225], v[78:81]
	v_mfma_f32_16x16x32_bf16 v[14:17], v[114:117], v[222:225], v[14:17]
	v_mfma_f32_16x16x32_bf16 v[70:73], v[106:109], v[230:233], v[70:73]
	v_mfma_f32_16x16x32_bf16 v[6:9], v[114:117], v[230:233], v[6:9]
	v_mfma_f32_16x16x32_bf16 v[94:97], v[110:113], v[186:189], v[94:97]
	v_mfma_f32_16x16x32_bf16 v[30:33], v[118:121], v[186:189], v[30:33]
	v_mfma_f32_16x16x32_bf16 v[86:89], v[110:113], v[218:221], v[86:89]
	v_mfma_f32_16x16x32_bf16 v[22:25], v[118:121], v[218:221], v[22:25]
	v_mfma_f32_16x16x32_bf16 v[78:81], v[110:113], v[226:229], v[78:81]
	v_mfma_f32_16x16x32_bf16 v[14:17], v[118:121], v[226:229], v[14:17]
	v_mfma_f32_16x16x32_bf16 v[70:73], v[110:113], v[234:237], v[70:73]
	v_mfma_f32_16x16x32_bf16 v[6:9], v[118:121], v[234:237], v[6:9]
	v_mfma_f32_16x16x32_bf16 v[90:93], v[122:125], v[182:185], v[90:93]
	v_mfma_f32_16x16x32_bf16 v[26:29], v[130:133], v[182:185], v[26:29]
	v_mfma_f32_16x16x32_bf16 v[82:85], v[122:125], v[190:193], v[82:85]
	v_mfma_f32_16x16x32_bf16 v[18:21], v[130:133], v[190:193], v[18:21]
	v_mfma_f32_16x16x32_bf16 v[74:77], v[122:125], v[222:225], v[74:77]
	v_mfma_f32_16x16x32_bf16 v[10:13], v[130:133], v[222:225], v[10:13]
	v_mfma_f32_16x16x32_bf16 v[66:69], v[122:125], v[230:233], v[66:69]
	v_mfma_f32_16x16x32_bf16 v[2:5], v[130:133], v[230:233], v[2:5]
	v_mfma_f32_16x16x32_bf16 v[90:93], v[126:129], v[186:189], v[90:93]
	v_mfma_f32_16x16x32_bf16 v[26:29], v[178:181], v[186:189], v[26:29]
	v_mfma_f32_16x16x32_bf16 v[82:85], v[126:129], v[218:221], v[82:85]
	v_mfma_f32_16x16x32_bf16 v[18:21], v[178:181], v[218:221], v[18:21]
	v_mfma_f32_16x16x32_bf16 v[74:77], v[126:129], v[226:229], v[74:77]
	v_mfma_f32_16x16x32_bf16 v[10:13], v[178:181], v[226:229], v[10:13]
	v_mfma_f32_16x16x32_bf16 v[66:69], v[126:129], v[234:237], v[66:69]
	v_mfma_f32_16x16x32_bf16 v[2:5], v[178:181], v[234:237], v[2:5]
	s_barrier
; #define PG8_STAGE(bufoff, gbase, voff) do { _Pragma("unroll") for (int _i = 0; _i < 2; ++_i) \
;         __builtin_amdgcn_global_load_lds((const unsigned*)((const char*)(gbase) + (voff)[_i]), (PG8_LAS unsigned*)(lds + (bufoff) + ldsw + _i * 8192), 16, 0, 0); } while (0)
; #define PG8_LDA(dst, b, h) do { _Pragma("unroll") for (int m = 0; m < 4; ++m) _Pragma("unroll") for (int k = 0; k < 2; ++k) dst[m][k] = *(const PG8_LAS bf16x8*)(lds + PG8_SA(b, h) + aoff + m * 2048 + k * 1024); } while (0)
; #define PG8_LDB(dst, b, h) do { _Pragma("unroll") for (int n = 0; n < 2; ++n) _Pragma("unroll") for (int k = 0; k < 2; ++k) dst[n][k] = *(const PG8_LAS bf16x8*)(lds + PG8_SB(b, h) + boff + n * 2048 + k * 1024); } while (0)
; #define PG8_MMA(ai, bj, At, Bt) do { __builtin_amdgcn_s_setprio(1); _Pragma("unroll") for (int m = 0; m < 4; ++m) _Pragma("unroll") for (int n = 0; n < 2; ++n) _Pragma("unroll") for (int k = 0; k < 2; ++k) \
;         acc[ai][bj][m][n] = __builtin_amdgcn_mfma_f32_16x16x32_bf16(Bt[n][k], At[m][k], acc[ai][bj][m][n], 0, 0, 0); __builtin_amdgcn_s_setprio(0); } while (0)
; #define PG8_WAIT_V(n) asm volatile("s_waitcnt vmcnt(" #n ")" ::: "memory")
; #define PG8_WAIT_L(n) asm volatile("s_waitcnt lgkmcnt(" #n ")" ::: "memory")
; #define PG8_BAR __builtin_amdgcn_s_barrier()
; #define PG8_SCHED __builtin_amdgcn_sched_barrier(0)
; template <class Epi, class Sched, bool ALIGN_EPI = false, bool SP2 = false>
; __device__ __forceinline__ void gemm_phase(PG8_LAS unsigned char* lds, const Gemm g, const Sched& S, const Epi& E, int wave_in) {
;     ...
;             PG8_LDB(B0, 1, 0); PG8_LDB(B1, 1, 1); PG8_SCHED; PG8_LDA(At, 1, 0); PG8_STAGE(PG8_SA(0, 1), a2 + hstepA, voffA);
;             PG8_WAIT_V(8); PG8_WAIT_L(0); PG8_BAR; PG8_MMA(0, 0, At, B0); PG8_MMA(0, 1, At, B1); PG8_BAR; PG8_SCHED;
;             PG8_LDA(At, 1, 1); PG8_STAGE(PG8_SB(1, 0), b3, voffB); PG8_STAGE(PG8_SB(1, 1), b3 + hstep, voffB); PG8_STAGE(PG8_SA(1, 0), a3, voffA);
;             PG8_WAIT_V(8); PG8_WAIT_L(0); PG8_BAR; PG8_MMA(1, 0, At, B0); PG8_MMA(1, 1, At, B1); PG8_BAR; PG8_SCHED;
	s_add_i32 s72, 0, 0x18000
	s_add_i32 s73, 0, 0x1c000
	v_add_u32_e32 v118, s72, v214
	v_add_u32_e32 v178, s73, v214
	ds_read_b128 v[106:109], v118
	ds_read_b128 v[110:113], v118 offset:1024
	ds_read_b128 v[114:117], v118 offset:2048
	ds_read_b128 v[118:121], v118 offset:3072
	ds_read_b128 v[122:125], v178
	ds_read_b128 v[126:129], v178 offset:1024
	ds_read_b128 v[130:133], v178 offset:2048
	ds_read_b128 v[178:181], v178 offset:3072
	s_add_u32 s52, s52, 0x80000
	s_addc_u32 s53, s53, 0
	s_mov_b32 m0, s60
	ds_read_b128 v[182:185], v217 offset:32768
	ds_read_b128 v[186:189], v217 offset:33792
	ds_read_b128 v[190:193], v217 offset:34816
	ds_read_b128 v[218:221], v217 offset:35840
	ds_read_b128 v[222:225], v217 offset:36864
	ds_read_b128 v[226:229], v217 offset:37888
	ds_read_b128 v[230:233], v217 offset:38912
	ds_read_b128 v[234:237], v217 offset:39936
	global_load_lds_dwordx4 v172, s[52:53]
	s_mov_b32 m0, s61
	s_nop 0
	global_load_lds_dwordx4 v170, s[52:53]
	s_waitcnt vmcnt(8)
	s_waitcnt lgkmcnt(0)
	s_barrier
	s_waitcnt lgkmcnt(0)
	v_mfma_f32_16x16x32_bf16 v[154:157], v[106:109], v[182:185], v[154:157]
	v_mfma_f32_16x16x32_bf16 v[62:65], v[114:117], v[182:185], v[62:65]
	v_mfma_f32_16x16x32_bf16 v[150:153], v[106:109], v[190:193], v[150:153]
	v_mfma_f32_16x16x32_bf16 v[54:57], v[114:117], v[190:193], v[54:57]
	v_mfma_f32_16x16x32_bf16 v[142:145], v[106:109], v[222:225], v[142:145]
	v_mfma_f32_16x16x32_bf16 v[46:49], v[114:117], v[222:225], v[46:49]
	v_mfma_f32_16x16x32_bf16 v[102:105], v[106:109], v[230:233], v[102:105]
	v_mfma_f32_16x16x32_bf16 v[38:41], v[114:117], v[230:233], v[38:41]
	v_mfma_f32_16x16x32_bf16 v[154:157], v[110:113], v[186:189], v[154:157]
	v_mfma_f32_16x16x32_bf16 v[62:65], v[118:121], v[186:189], v[62:65]
	v_mfma_f32_16x16x32_bf16 v[150:153], v[110:113], v[218:221], v[150:153]
	v_mfma_f32_16x16x32_bf16 v[54:57], v[118:121], v[218:221], v[54:57]
	v_mfma_f32_16x16x32_bf16 v[142:145], v[110:113], v[226:229], v[142:145]
	v_mfma_f32_16x16x32_bf16 v[46:49], v[118:121], v[226:229], v[46:49]
	v_mfma_f32_16x16x32_bf16 v[102:105], v[110:113], v[234:237], v[102:105]
	v_mfma_f32_16x16x32_bf16 v[38:41], v[118:121], v[234:237], v[38:41]
	v_mfma_f32_16x16x32_bf16 v[134:137], v[122:125], v[182:185], v[134:137]
	v_mfma_f32_16x16x32_bf16 v[58:61], v[130:133], v[182:185], v[58:61]
	v_mfma_f32_16x16x32_bf16 v[146:149], v[122:125], v[190:193], v[146:149]
	v_mfma_f32_16x16x32_bf16 v[50:53], v[130:133], v[190:193], v[50:53]
	v_mfma_f32_16x16x32_bf16 v[138:141], v[122:125], v[222:225], v[138:141]
	v_mfma_f32_16x16x32_bf16 v[42:45], v[130:133], v[222:225], v[42:45]
	v_mfma_f32_16x16x32_bf16 v[98:101], v[122:125], v[230:233], v[98:101]
	v_mfma_f32_16x16x32_bf16 v[34:37], v[130:133], v[230:233], v[34:37]
	v_mfma_f32_16x16x32_bf16 v[134:137], v[126:129], v[186:189], v[134:137]
	v_mfma_f32_16x16x32_bf16 v[58:61], v[178:181], v[186:189], v[58:61]
	v_mfma_f32_16x16x32_bf16 v[146:149], v[126:129], v[218:221], v[146:149]
	v_mfma_f32_16x16x32_bf16 v[50:53], v[178:181], v[218:221], v[50:53]
	v_mfma_f32_16x16x32_bf16 v[138:141], v[126:129], v[226:229], v[138:141]
	v_mfma_f32_16x16x32_bf16 v[42:45], v[178:181], v[226:229], v[42:45]
	v_mfma_f32_16x16x32_bf16 v[98:101], v[126:129], v[234:237], v[98:101]
	v_mfma_f32_16x16x32_bf16 v[34:37], v[178:181], v[234:237], v[34:37]
	s_barrier
	s_add_i32 s52, s72, s57
	s_mov_b32 m0, s52
	ds_read_b128 v[182:185], v217 offset:49152
	ds_read_b128 v[186:189], v217 offset:50176
	ds_read_b128 v[190:193], v217 offset:51200
	ds_read_b128 v[218:221], v217 offset:52224
	ds_read_b128 v[222:225], v217 offset:53248
	ds_read_b128 v[226:229], v217 offset:54272
	ds_read_b128 v[230:233], v217 offset:55296
	ds_read_b128 v[234:237], v217 offset:56320
	global_load_lds_dwordx4 v0, vcc
	s_add_i32 m0, s52, 0x2000
	s_add_u32 s50, s50, 0x80080
	s_addc_u32 s51, s51, 0
	s_add_i32 s52, s73, s57
	global_load_lds_dwordx4 v168, vcc
	s_mov_b32 m0, s52
	s_nop 0
	global_load_lds_dwordx4 v0, s[50:51]
	s_add_i32 m0, s52, 0x2000
	s_nop 0
	global_load_lds_dwordx4 v168, s[50:51]
	s_mov_b32 m0, s62
	s_nop 0
	global_load_lds_dwordx4 v172, s[98:99]
	s_mov_b32 m0, s63
	s_nop 0
	global_load_lds_dwordx4 v170, s[98:99]
	s_waitcnt vmcnt(8)
	s_waitcnt lgkmcnt(0)
	s_barrier
	s_waitcnt lgkmcnt(0)
	v_mfma_f32_16x16x32_bf16 v[94:97], v[106:109], v[182:185], v[94:97]
	v_mfma_f32_16x16x32_bf16 v[30:33], v[114:117], v[182:185], v[30:33]
	v_mfma_f32_16x16x32_bf16 v[86:89], v[106:109], v[190:193], v[86:89]
	v_mfma_f32_16x16x32_bf16 v[22:25], v[114:117], v[190:193], v[22:25]
	v_mfma_f32_16x16x32_bf16 v[78:81], v[106:109], v[222:225], v[78:81]
	v_mfma_f32_16x16x32_bf16 v[14:17], v[114:117], v[222:225], v[14:17]
	v_mfma_f32_16x16x32_bf16 v[70:73], v[106:109], v[230:233], v[70:73]
	v_mfma_f32_16x16x32_bf16 v[6:9], v[114:117], v[230:233], v[6:9]
	v_mfma_f32_16x16x32_bf16 v[94:97], v[110:113], v[186:189], v[94:97]
	v_mfma_f32_16x16x32_bf16 v[30:33], v[118:121], v[186:189], v[30:33]
	v_mfma_f32_16x16x32_bf16 v[86:89], v[110:113], v[218:221], v[86:89]
	v_mfma_f32_16x16x32_bf16 v[22:25], v[118:121], v[218:221], v[22:25]
	v_mfma_f32_16x16x32_bf16 v[78:81], v[110:113], v[226:229], v[78:81]
	v_mfma_f32_16x16x32_bf16 v[14:17], v[118:121], v[226:229], v[14:17]
	v_mfma_f32_16x16x32_bf16 v[70:73], v[110:113], v[234:237], v[70:73]
	v_mfma_f32_16x16x32_bf16 v[6:9], v[118:121], v[234:237], v[6:9]
	v_mfma_f32_16x16x32_bf16 v[90:93], v[122:125], v[182:185], v[90:93]
	v_mfma_f32_16x16x32_bf16 v[26:29], v[130:133], v[182:185], v[26:29]
	v_mfma_f32_16x16x32_bf16 v[82:85], v[122:125], v[190:193], v[82:85]
	v_mfma_f32_16x16x32_bf16 v[18:21], v[130:133], v[190:193], v[18:21]
	v_mfma_f32_16x16x32_bf16 v[74:77], v[122:125], v[222:225], v[74:77]
	v_mfma_f32_16x16x32_bf16 v[10:13], v[130:133], v[222:225], v[10:13]
	v_mfma_f32_16x16x32_bf16 v[66:69], v[122:125], v[230:233], v[66:69]
	v_mfma_f32_16x16x32_bf16 v[2:5], v[130:133], v[230:233], v[2:5]
	v_mfma_f32_16x16x32_bf16 v[90:93], v[126:129], v[186:189], v[90:93]
	v_mfma_f32_16x16x32_bf16 v[26:29], v[178:181], v[186:189], v[26:29]
	v_mfma_f32_16x16x32_bf16 v[82:85], v[126:129], v[218:221], v[82:85]
	v_mfma_f32_16x16x32_bf16 v[18:21], v[178:181], v[218:221], v[18:21]
	v_mfma_f32_16x16x32_bf16 v[74:77], v[126:129], v[226:229], v[74:77]
	v_mfma_f32_16x16x32_bf16 v[10:13], v[178:181], v[226:229], v[10:13]
	v_mfma_f32_16x16x32_bf16 v[66:69], v[126:129], v[234:237], v[66:69]
	v_mfma_f32_16x16x32_bf16 v[2:5], v[178:181], v[234:237], v[2:5]
	s_barrier
	s_add_i32 s71, s71, 2
	s_add_u32 s48, s48, 0x100
	s_addc_u32 s49, s49, 0
	s_add_u32 s69, s69, 0x100
	s_addc_u32 s70, s70, 0
	s_cmp_gt_u32 s71, 29
	s_cbranch_scc0 .LBB0_43
	s_and_b64 vcc, exec, s[24:25]
	s_cbranch_vccz .LBB0_46
	s_barrier

; #define PG8_STAGE(bufoff, gbase, voff) do { _Pragma("unroll") for (int _i = 0; _i < 2; ++_i) \
;         __builtin_amdgcn_global_load_lds((const unsigned*)((const char*)(gbase) + (voff)[_i]), (PG8_LAS unsigned*)(lds + (bufoff) + ldsw + _i * 8192), 16, 0, 0); } while (0)
; #define PG8_LDA(dst, b, h) do { _Pragma("unroll") for (int m = 0; m < 4; ++m) _Pragma("unroll") for (int k = 0; k < 2; ++k) dst[m][k] = *(const PG8_LAS bf16x8*)(lds + PG8_SA(b, h) + aoff + m * 2048 + k * 1024); } while (0)
; #define PG8_LDB(dst, b, h) do { _Pragma("unroll") for (int n = 0; n < 2; ++n) _Pragma("unroll") for (int k = 0; k < 2; ++k) dst[n][k] = *(const PG8_LAS bf16x8*)(lds + PG8_SB(b, h) + boff + n * 2048 + k * 1024); } while (0)
; #define PG8_SCHED __builtin_amdgcn_sched_barrier(0)
; template <class Epi, class Sched, bool ALIGN_EPI = false, bool SP2 = false>
; __device__ __forceinline__ void gemm_phase(PG8_LAS unsigned char* lds, const Gemm g, const Sched& S, const Epi& E, int wave_in) {
;     ...
;             const bool last = (t == nt - 2);
;             const char* a1 = cA + (size_t)(t + 1) * kstep;
;             const char* a2 = last ? nA : cA + (size_t)(t + 2) * kstep; const char* b2 = last ? nB : cB + (size_t)(t + 2) * kstep;
;             const char* a3 = a2 + kstep; const char* b3 = b2 + kstep;
;             if (last && has_next) S.a_ready(nxt);
;             if constexpr (SP2) {
;             PG8_LDB(B0, 0, 0); PG8_LDB(B1, 0, 1); PG8_SCHED; PG8_LDA(At, 0, 0); PG8_STAGE(PG8_SA(1, 1), a1 + hstepA, voffA);
;     ...
; #pragma unroll
;         for (int a = 0; a < 2; ++a)
; #pragma unroll
;             for (int b = 0; b < 2; ++b)
; #pragma unroll
;                 for (int m = 0; m < 4; ++m)
; #pragma unroll
;                     for (int n = 0; n < 2; ++n) acc[a][b][m][n] = (f32x4){0.f, 0.f, 0.f, 0.f};
;         cur = nxt; cA = nA; cB = nB; ++ui;
.LBB0_83:
	s_ashr_i32 s17, s16, 31
	s_lshl_b64 s[18:19], s[16:17], 20
	v_readlane_b32 s20, v253, 62
	v_readlane_b32 s21, v253, 63
	s_add_u32 s18, s20, s18
	s_addc_u32 s19, s21, s19
	s_and_b64 s[20:21], s[4:5], exec
	s_cselect_b32 s17, s19, s23
	s_cselect_b32 s42, s18, s22
	s_ashr_i32 s11, s10, 31
	s_lshl_b64 s[20:21], s[10:11], 19
	s_add_u32 s20, s28, s20
	s_addc_u32 s21, s29, s21
	s_and_b64 s[26:27], s[4:5], exec
	s_cselect_b32 s11, s21, s25
	s_cselect_b32 s43, s20, s24
	s_add_u32 s22, s22, 0x80080
	s_addc_u32 s23, s23, 0
	s_add_u32 s44, s24, 0x100
	v_mov_b32_e32 v2, 0
	s_addc_u32 s45, s25, 0
	s_mov_b32 s46, -2
	v_mov_b32_e32 v3, v2
	v_mov_b32_e32 v4, v2
	v_mov_b32_e32 v5, v2
	v_mov_b32_e32 v6, v2
	v_mov_b32_e32 v7, v2
	v_mov_b32_e32 v8, v2
	v_mov_b32_e32 v9, v2
	v_mov_b32_e32 v14, v2
	v_mov_b32_e32 v15, v2
	v_mov_b32_e32 v16, v2
	v_mov_b32_e32 v17, v2
	v_mov_b32_e32 v18, v2
	v_mov_b32_e32 v19, v2
	s_waitcnt vmcnt(0)
	v_mov_b32_e32 v20, v2
	v_mov_b32_e32 v21, v2
	v_mov_b32_e32 v30, v2
	v_mov_b32_e32 v31, v2
	v_mov_b32_e32 v32, v2
	v_mov_b32_e32 v33, v2
	v_mov_b32_e32 v34, v2
	v_mov_b32_e32 v35, v2
	v_mov_b32_e32 v36, v2
	v_mov_b32_e32 v37, v2
	v_mov_b32_e32 v46, v2
	v_mov_b32_e32 v47, v2
	v_mov_b32_e32 v48, v2
	v_mov_b32_e32 v49, v2
	v_mov_b32_e32 v50, v2
	v_mov_b32_e32 v51, v2
	v_mov_b32_e32 v52, v2
	v_mov_b32_e32 v53, v2
	v_mov_b32_e32 v10, v2
	v_mov_b32_e32 v11, v2
	v_mov_b32_e32 v12, v2
	v_mov_b32_e32 v13, v2
	v_mov_b32_e32 v22, v2
	v_mov_b32_e32 v23, v2
	v_mov_b32_e32 v24, v2
	v_mov_b32_e32 v25, v2
	v_mov_b32_e32 v26, v2
	v_mov_b32_e32 v27, v2
	v_mov_b32_e32 v28, v2
	v_mov_b32_e32 v29, v2
	v_mov_b32_e32 v38, v2
	v_mov_b32_e32 v39, v2
	v_mov_b32_e32 v40, v2
	v_mov_b32_e32 v41, v2
	v_mov_b32_e32 v42, v2
	v_mov_b32_e32 v43, v2
	v_mov_b32_e32 v44, v2
	v_mov_b32_e32 v45, v2
	v_mov_b32_e32 v54, v2
	v_mov_b32_e32 v55, v2
	v_mov_b32_e32 v56, v2
	v_mov_b32_e32 v57, v2
	v_mov_b32_e32 v58, v2
	v_mov_b32_e32 v59, v2
	v_mov_b32_e32 v60, v2
	v_mov_b32_e32 v61, v2
	v_mov_b32_e32 v62, v2
	v_mov_b32_e32 v63, v2
	v_mov_b32_e32 v64, v2
	v_mov_b32_e32 v65, v2
	v_mov_b32_e32 v66, v2
	v_mov_b32_e32 v67, v2
	v_mov_b32_e32 v68, v2
	v_mov_b32_e32 v69, v2
	v_mov_b32_e32 v70, v2
	v_mov_b32_e32 v71, v2
	v_mov_b32_e32 v72, v2
	v_mov_b32_e32 v73, v2
	v_mov_b32_e32 v78, v2
	v_mov_b32_e32 v79, v2
	v_mov_b32_e32 v80, v2
	v_mov_b32_e32 v81, v2
	v_mov_b32_e32 v82, v2
	v_mov_b32_e32 v83, v2
	v_mov_b32_e32 v84, v2
	v_mov_b32_e32 v85, v2
	v_mov_b32_e32 v94, v2
	v_mov_b32_e32 v95, v2
	v_mov_b32_e32 v96, v2
	v_mov_b32_e32 v97, v2
	v_mov_b32_e32 v98, v2
	v_mov_b32_e32 v99, v2
	v_mov_b32_e32 v100, v2
	v_mov_b32_e32 v101, v2
	v_mov_b32_e32 v110, v2
	v_mov_b32_e32 v111, v2
	v_mov_b32_e32 v112, v2
	v_mov_b32_e32 v113, v2
	v_mov_b32_e32 v114, v2
	v_mov_b32_e32 v115, v2
	v_mov_b32_e32 v116, v2
	v_mov_b32_e32 v117, v2
	v_mov_b32_e32 v74, v2
	v_mov_b32_e32 v75, v2
	v_mov_b32_e32 v76, v2
	v_mov_b32_e32 v77, v2
	v_mov_b32_e32 v86, v2
	v_mov_b32_e32 v87, v2
	v_mov_b32_e32 v88, v2
	v_mov_b32_e32 v89, v2
	v_mov_b32_e32 v90, v2
	v_mov_b32_e32 v91, v2
	v_mov_b32_e32 v92, v2
	v_mov_b32_e32 v93, v2
	v_mov_b32_e32 v102, v2
	v_mov_b32_e32 v103, v2
	v_mov_b32_e32 v104, v2
	v_mov_b32_e32 v105, v2
	v_mov_b32_e32 v106, v2
	v_mov_b32_e32 v107, v2
	v_mov_b32_e32 v108, v2
	v_mov_b32_e32 v109, v2
	v_mov_b32_e32 v118, v2
	v_mov_b32_e32 v119, v2
	v_mov_b32_e32 v120, v2
	v_mov_b32_e32 v121, v2
	v_mov_b32_e32 v122, v2
	v_mov_b32_e32 v123, v2
	v_mov_b32_e32 v124, v2
	v_mov_b32_e32 v125, v2
	v_mov_b32_e32 v126, v2
	v_mov_b32_e32 v127, v2
	v_mov_b32_e32 v128, v2
	v_mov_b32_e32 v129, v2
	s_nop 0
	s_nop 0
	s_nop 0
	s_nop 0
	s_nop 0
	s_nop 0
	s_nop 0
	s_nop 0
	s_nop 0
	s_nop 0
.LBB0_84:
	s_add_u32 s24, s22, 0xfff80080
	s_addc_u32 s25, s23, -1
	s_add_i32 s47, 0, 0x10000
	s_cmp_eq_u32 s46, 12
	s_cselect_b32 s27, s17, s25
	s_cselect_b32 s26, s42, s24
	v_add_u32_e32 v144, s47, v147
	s_cselect_b32 s25, s11, s45
	s_cselect_b32 s24, s43, s44
	s_add_i32 s50, 0, 0x14000
	ds_read_b128 v[140:143], v144
	ds_read_b128 v[150:153], v144 offset:1024
	ds_read_b128 v[154:157], v144 offset:2048
	ds_read_b128 v[168:171], v144 offset:3072
	v_add_u32_e32 v144, s50, v147
	ds_read_b128 v[172:175], v144
	ds_read_b128 v[176:179], v144 offset:1024
	ds_read_b128 v[180:183], v144 offset:2048
	ds_read_b128 v[184:187], v144 offset:3072
	v_lshl_add_u64 v[144:145], s[22:23], 0, v[136:137]
	s_add_i32 m0, s31, 0xc000
	ds_read_b128 v[188:191], v149
	ds_read_b128 v[212:215], v149 offset:1024
	ds_read_b128 v[216:219], v149 offset:2048
	ds_read_b128 v[220:223], v149 offset:3072
	ds_read_b128 v[224:227], v149 offset:4096
	ds_read_b128 v[228:231], v149 offset:5120
	ds_read_b128 v[232:235], v149 offset:6144
	ds_read_b128 v[236:239], v149 offset:7168
	global_load_lds_dwordx4 v[144:145], off
	v_lshl_add_u64 v[144:145], s[22:23], 0, v[138:139]
	s_add_i32 m0, s31, 0xe000
	s_nop 0
	global_load_lds_dwordx4 v[144:145], off
	s_waitcnt vmcnt(8)
	s_waitcnt lgkmcnt(0)
	s_barrier
; #define PG8_STAGE(bufoff, gbase, voff) do { _Pragma("unroll") for (int _i = 0; _i < 2; ++_i) \
;         __builtin_amdgcn_global_load_lds((const unsigned*)((const char*)(gbase) + (voff)[_i]), (PG8_LAS unsigned*)(lds + (bufoff) + ldsw + _i * 8192), 16, 0, 0); } while (0)
; #define PG8_LDA(dst, b, h) do { _Pragma("unroll") for (int m = 0; m < 4; ++m) _Pragma("unroll") for (int k = 0; k < 2; ++k) dst[m][k] = *(const PG8_LAS bf16x8*)(lds + PG8_SA(b, h) + aoff + m * 2048 + k * 1024); } while (0)
; #define PG8_LDB(dst, b, h) do { _Pragma("unroll") for (int n = 0; n < 2; ++n) _Pragma("unroll") for (int k = 0; k < 2; ++k) dst[n][k] = *(const PG8_LAS bf16x8*)(lds + PG8_SB(b, h) + boff + n * 2048 + k * 1024); } while (0)
; #define PG8_MMA(ai, bj, At, Bt) do { __builtin_amdgcn_s_setprio(1); _Pragma("unroll") for (int m = 0; m < 4; ++m) _Pragma("unroll") for (int n = 0; n < 2; ++n) _Pragma("unroll") for (int k = 0; k < 2; ++k) \
;         acc[ai][bj][m][n] = __builtin_amdgcn_mfma_f32_16x16x32_bf16(Bt[n][k], At[m][k], acc[ai][bj][m][n], 0, 0, 0); __builtin_amdgcn_s_setprio(0); } while (0)
; #define PG8_WAIT_V(n) asm volatile("s_waitcnt vmcnt(" #n ")" ::: "memory")
; #define PG8_WAIT_L(n) asm volatile("s_waitcnt lgkmcnt(" #n ")" ::: "memory")
; #define PG8_BAR __builtin_amdgcn_s_barrier()
; #define PG8_SCHED __builtin_amdgcn_sched_barrier(0)
; template <class Epi, class Sched, bool ALIGN_EPI = false, bool SP2 = false>
; __device__ __forceinline__ void gemm_phase(PG8_LAS unsigned char* lds, const Gemm g, const Sched& S, const Epi& E, int wave_in) {
;     ...
;             PG8_LDB(B0, 0, 0); PG8_LDB(B1, 0, 1); PG8_SCHED; PG8_LDA(At, 0, 0); PG8_STAGE(PG8_SA(1, 1), a1 + hstepA, voffA);
;             PG8_WAIT_V(8); PG8_WAIT_L(0); PG8_BAR; PG8_MMA(0, 0, At, B0); PG8_MMA(0, 1, At, B1); PG8_BAR; PG8_SCHED;
;             PG8_LDA(At, 0, 1); PG8_STAGE(PG8_SB(0, 0), b2, voffB); PG8_STAGE(PG8_SB(0, 1), b2 + hstep, voffB); PG8_STAGE(PG8_SA(0, 0), a2, voffA);
;             PG8_WAIT_V(8); PG8_WAIT_L(0); PG8_BAR; PG8_MMA(1, 0, At, B0); PG8_MMA(1, 1, At, B1); PG8_BAR; PG8_SCHED;
	s_waitcnt lgkmcnt(0)
	v_mfma_f32_16x16x32_bf16 v[126:129], v[140:143], v[188:191], v[126:129]
	v_mfma_f32_16x16x32_bf16 v[122:125], v[154:157], v[188:191], v[122:125]
	v_mfma_f32_16x16x32_bf16 v[118:121], v[140:143], v[216:219], v[118:121]
	v_mfma_f32_16x16x32_bf16 v[106:109], v[154:157], v[216:219], v[106:109]
	v_mfma_f32_16x16x32_bf16 v[102:105], v[140:143], v[224:227], v[102:105]
	v_mfma_f32_16x16x32_bf16 v[90:93], v[154:157], v[224:227], v[90:93]
	v_mfma_f32_16x16x32_bf16 v[86:89], v[140:143], v[232:235], v[86:89]
	v_mfma_f32_16x16x32_bf16 v[74:77], v[154:157], v[232:235], v[74:77]
	v_mfma_f32_16x16x32_bf16 v[126:129], v[150:153], v[212:215], v[126:129]
	v_mfma_f32_16x16x32_bf16 v[122:125], v[168:171], v[212:215], v[122:125]
	v_mfma_f32_16x16x32_bf16 v[118:121], v[150:153], v[220:223], v[118:121]
	v_mfma_f32_16x16x32_bf16 v[106:109], v[168:171], v[220:223], v[106:109]
	v_mfma_f32_16x16x32_bf16 v[102:105], v[150:153], v[228:231], v[102:105]
	v_mfma_f32_16x16x32_bf16 v[90:93], v[168:171], v[228:231], v[90:93]
	v_mfma_f32_16x16x32_bf16 v[86:89], v[150:153], v[236:239], v[86:89]
	v_mfma_f32_16x16x32_bf16 v[74:77], v[168:171], v[236:239], v[74:77]
	v_mfma_f32_16x16x32_bf16 v[114:117], v[172:175], v[188:191], v[114:117]
	v_mfma_f32_16x16x32_bf16 v[110:113], v[180:183], v[188:191], v[110:113]
	v_mfma_f32_16x16x32_bf16 v[98:101], v[172:175], v[216:219], v[98:101]
	v_mfma_f32_16x16x32_bf16 v[94:97], v[180:183], v[216:219], v[94:97]
	v_mfma_f32_16x16x32_bf16 v[82:85], v[172:175], v[224:227], v[82:85]
	v_mfma_f32_16x16x32_bf16 v[78:81], v[180:183], v[224:227], v[78:81]
	v_mfma_f32_16x16x32_bf16 v[70:73], v[172:175], v[232:235], v[70:73]
	v_mfma_f32_16x16x32_bf16 v[66:69], v[180:183], v[232:235], v[66:69]
	v_mfma_f32_16x16x32_bf16 v[114:117], v[176:179], v[212:215], v[114:117]
	v_mfma_f32_16x16x32_bf16 v[110:113], v[184:187], v[212:215], v[110:113]
	v_mfma_f32_16x16x32_bf16 v[98:101], v[176:179], v[220:223], v[98:101]
	v_mfma_f32_16x16x32_bf16 v[94:97], v[184:187], v[220:223], v[94:97]
	v_mfma_f32_16x16x32_bf16 v[82:85], v[176:179], v[228:231], v[82:85]
	v_mfma_f32_16x16x32_bf16 v[78:81], v[184:187], v[228:231], v[78:81]
	v_mfma_f32_16x16x32_bf16 v[70:73], v[176:179], v[236:239], v[70:73]
	v_mfma_f32_16x16x32_bf16 v[66:69], v[184:187], v[236:239], v[66:69]
	s_barrier
	s_add_i32 s47, s47, s30
	v_lshl_add_u64 v[144:145], s[24:25], 0, v[0:1]
	s_mov_b32 m0, s47
	ds_read_b128 v[188:191], v149 offset:16384
	ds_read_b128 v[212:215], v149 offset:17408
	ds_read_b128 v[216:219], v149 offset:18432
	ds_read_b128 v[220:223], v149 offset:19456
	ds_read_b128 v[224:227], v149 offset:20480
	ds_read_b128 v[228:231], v149 offset:21504
	ds_read_b128 v[232:235], v149 offset:22528
	ds_read_b128 v[236:239], v149 offset:23552
	global_load_lds_dwordx4 v[144:145], off
	s_add_i32 m0, s47, 0x2000
	s_add_u32 s48, s24, 0x40000
	v_lshl_add_u64 v[192:193], s[24:25], 0, v[130:131]
	s_addc_u32 s49, s25, 0
	s_add_i32 s47, s50, s30
	global_load_lds_dwordx4 v[192:193], off
	v_lshl_add_u64 v[240:241], s[48:49], 0, v[0:1]
	s_mov_b32 m0, s47
	v_lshl_add_u64 v[242:243], s[26:27], 0, v[132:133]
	global_load_lds_dwordx4 v[240:241], off
	v_lshl_add_u64 v[240:241], s[48:49], 0, v[130:131]
	s_add_i32 m0, s47, 0x2000
	s_nop 0
	global_load_lds_dwordx4 v[240:241], off
	v_lshl_add_u64 v[240:241], s[26:27], 0, v[134:135]
	s_mov_b32 m0, s31
	s_nop 0
	global_load_lds_dwordx4 v[240:241], off
	s_mov_b32 m0, s34
	s_nop 0
	global_load_lds_dwordx4 v[242:243], off
	s_waitcnt vmcnt(8)
	s_waitcnt lgkmcnt(0)
	s_barrier
	s_waitcnt lgkmcnt(0)
	v_mfma_f32_16x16x32_bf16 v[62:65], v[140:143], v[188:191], v[62:65]
	v_mfma_f32_16x16x32_bf16 v[58:61], v[154:157], v[188:191], v[58:61]
	v_mfma_f32_16x16x32_bf16 v[54:57], v[140:143], v[216:219], v[54:57]
	v_mfma_f32_16x16x32_bf16 v[42:45], v[154:157], v[216:219], v[42:45]
	v_mfma_f32_16x16x32_bf16 v[38:41], v[140:143], v[224:227], v[38:41]
	v_mfma_f32_16x16x32_bf16 v[26:29], v[154:157], v[224:227], v[26:29]
	v_mfma_f32_16x16x32_bf16 v[22:25], v[140:143], v[232:235], v[22:25]
	v_mfma_f32_16x16x32_bf16 v[10:13], v[154:157], v[232:235], v[10:13]
	v_mfma_f32_16x16x32_bf16 v[62:65], v[150:153], v[212:215], v[62:65]
	v_mfma_f32_16x16x32_bf16 v[58:61], v[168:171], v[212:215], v[58:61]
	v_mfma_f32_16x16x32_bf16 v[54:57], v[150:153], v[220:223], v[54:57]
	v_mfma_f32_16x16x32_bf16 v[42:45], v[168:171], v[220:223], v[42:45]
	v_mfma_f32_16x16x32_bf16 v[38:41], v[150:153], v[228:231], v[38:41]
	v_mfma_f32_16x16x32_bf16 v[26:29], v[168:171], v[228:231], v[26:29]
	v_mfma_f32_16x16x32_bf16 v[22:25], v[150:153], v[236:239], v[22:25]
	v_mfma_f32_16x16x32_bf16 v[10:13], v[168:171], v[236:239], v[10:13]
	v_mfma_f32_16x16x32_bf16 v[50:53], v[172:175], v[188:191], v[50:53]
	v_mfma_f32_16x16x32_bf16 v[46:49], v[180:183], v[188:191], v[46:49]
	v_mfma_f32_16x16x32_bf16 v[34:37], v[172:175], v[216:219], v[34:37]
	v_mfma_f32_16x16x32_bf16 v[30:33], v[180:183], v[216:219], v[30:33]
	v_mfma_f32_16x16x32_bf16 v[18:21], v[172:175], v[224:227], v[18:21]
	v_mfma_f32_16x16x32_bf16 v[14:17], v[180:183], v[224:227], v[14:17]
	v_mfma_f32_16x16x32_bf16 v[6:9], v[172:175], v[232:235], v[6:9]
	v_mfma_f32_16x16x32_bf16 v[2:5], v[180:183], v[232:235], v[2:5]
	v_mfma_f32_16x16x32_bf16 v[50:53], v[176:179], v[212:215], v[50:53]
	v_mfma_f32_16x16x32_bf16 v[46:49], v[184:187], v[212:215], v[46:49]
	v_mfma_f32_16x16x32_bf16 v[34:37], v[176:179], v[220:223], v[34:37]
	v_mfma_f32_16x16x32_bf16 v[30:33], v[184:187], v[220:223], v[30:33]
	v_mfma_f32_16x16x32_bf16 v[18:21], v[176:179], v[228:231], v[18:21]
	v_mfma_f32_16x16x32_bf16 v[14:17], v[184:187], v[228:231], v[14:17]
	v_mfma_f32_16x16x32_bf16 v[6:9], v[176:179], v[236:239], v[6:9]
	v_mfma_f32_16x16x32_bf16 v[2:5], v[184:187], v[236:239], v[2:5]
	s_barrier
; #define PG8_STAGE(bufoff, gbase, voff) do { _Pragma("unroll") for (int _i = 0; _i < 2; ++_i) \
;         __builtin_amdgcn_global_load_lds((const unsigned*)((const char*)(gbase) + (voff)[_i]), (PG8_LAS unsigned*)(lds + (bufoff) + ldsw + _i * 8192), 16, 0, 0); } while (0)
; #define PG8_LDA(dst, b, h) do { _Pragma("unroll") for (int m = 0; m < 4; ++m) _Pragma("unroll") for (int k = 0; k < 2; ++k) dst[m][k] = *(const PG8_LAS bf16x8*)(lds + PG8_SA(b, h) + aoff + m * 2048 + k * 1024); } while (0)
; #define PG8_LDB(dst, b, h) do { _Pragma("unroll") for (int n = 0; n < 2; ++n) _Pragma("unroll") for (int k = 0; k < 2; ++k) dst[n][k] = *(const PG8_LAS bf16x8*)(lds + PG8_SB(b, h) + boff + n * 2048 + k * 1024); } while (0)
; #define PG8_MMA(ai, bj, At, Bt) do { __builtin_amdgcn_s_setprio(1); _Pragma("unroll") for (int m = 0; m < 4; ++m) _Pragma("unroll") for (int n = 0; n < 2; ++n) _Pragma("unroll") for (int k = 0; k < 2; ++k) \
;         acc[ai][bj][m][n] = __builtin_amdgcn_mfma_f32_16x16x32_bf16(Bt[n][k], At[m][k], acc[ai][bj][m][n], 0, 0, 0); __builtin_amdgcn_s_setprio(0); } while (0)
; #define PG8_WAIT_V(n) asm volatile("s_waitcnt vmcnt(" #n ")" ::: "memory")
; #define PG8_WAIT_L(n) asm volatile("s_waitcnt lgkmcnt(" #n ")" ::: "memory")
; #define PG8_BAR __builtin_amdgcn_s_barrier()
; #define PG8_SCHED __builtin_amdgcn_sched_barrier(0)
; template <class Epi, class Sched, bool ALIGN_EPI = false, bool SP2 = false>
; __device__ __forceinline__ void gemm_phase(PG8_LAS unsigned char* lds, const Gemm g, const Sched& S, const Epi& E, int wave_in) {
;     ...
;             PG8_LDB(B0, 1, 0); PG8_LDB(B1, 1, 1); PG8_SCHED; PG8_LDA(At, 1, 0); PG8_STAGE(PG8_SA(0, 1), a2 + hstepA, voffA);
;             PG8_WAIT_V(8); PG8_WAIT_L(0); PG8_BAR; PG8_MMA(0, 0, At, B0); PG8_MMA(0, 1, At, B1); PG8_BAR; PG8_SCHED;
	s_add_i32 s47, 0, 0x18000
	s_add_i32 s48, 0, 0x1c000
	v_add_u32_e32 v168, s47, v147
	v_add_u32_e32 v184, s48, v147
	ds_read_b128 v[140:143], v168
	ds_read_b128 v[150:153], v168 offset:1024
	ds_read_b128 v[154:157], v168 offset:2048
	ds_read_b128 v[168:171], v168 offset:3072
	ds_read_b128 v[172:175], v184
	ds_read_b128 v[176:179], v184 offset:1024
	ds_read_b128 v[180:183], v184 offset:2048
	ds_read_b128 v[184:187], v184 offset:3072
	s_add_u32 s26, s26, 0x80000
	s_addc_u32 s27, s27, 0
	s_mov_b32 m0, s35
	v_lshl_add_u64 v[244:245], s[26:27], 0, v[134:135]
	ds_read_b128 v[188:191], v149 offset:32768
	ds_read_b128 v[212:215], v149 offset:33792
	ds_read_b128 v[216:219], v149 offset:34816
	ds_read_b128 v[220:223], v149 offset:35840
	ds_read_b128 v[224:227], v149 offset:36864
	ds_read_b128 v[228:231], v149 offset:37888
	ds_read_b128 v[232:235], v149 offset:38912
	ds_read_b128 v[236:239], v149 offset:39936
	global_load_lds_dwordx4 v[244:245], off
	v_lshl_add_u64 v[244:245], s[26:27], 0, v[132:133]
	s_mov_b32 m0, s36
	s_nop 0
	global_load_lds_dwordx4 v[244:245], off
	s_waitcnt vmcnt(8)
	s_waitcnt lgkmcnt(0)
	s_barrier
	s_waitcnt lgkmcnt(0)
	v_mfma_f32_16x16x32_bf16 v[126:129], v[140:143], v[188:191], v[126:129]
	v_mfma_f32_16x16x32_bf16 v[122:125], v[154:157], v[188:191], v[122:125]
	v_mfma_f32_16x16x32_bf16 v[118:121], v[140:143], v[216:219], v[118:121]
	v_mfma_f32_16x16x32_bf16 v[106:109], v[154:157], v[216:219], v[106:109]
	v_mfma_f32_16x16x32_bf16 v[102:105], v[140:143], v[224:227], v[102:105]
	v_mfma_f32_16x16x32_bf16 v[90:93], v[154:157], v[224:227], v[90:93]
	v_mfma_f32_16x16x32_bf16 v[86:89], v[140:143], v[232:235], v[86:89]
	v_mfma_f32_16x16x32_bf16 v[74:77], v[154:157], v[232:235], v[74:77]
	v_mfma_f32_16x16x32_bf16 v[126:129], v[150:153], v[212:215], v[126:129]
	v_mfma_f32_16x16x32_bf16 v[122:125], v[168:171], v[212:215], v[122:125]
	v_mfma_f32_16x16x32_bf16 v[118:121], v[150:153], v[220:223], v[118:121]
	v_mfma_f32_16x16x32_bf16 v[106:109], v[168:171], v[220:223], v[106:109]
	v_mfma_f32_16x16x32_bf16 v[102:105], v[150:153], v[228:231], v[102:105]
	v_mfma_f32_16x16x32_bf16 v[90:93], v[168:171], v[228:231], v[90:93]
	v_mfma_f32_16x16x32_bf16 v[86:89], v[150:153], v[236:239], v[86:89]
	v_mfma_f32_16x16x32_bf16 v[74:77], v[168:171], v[236:239], v[74:77]
	v_mfma_f32_16x16x32_bf16 v[114:117], v[172:175], v[188:191], v[114:117]
	v_mfma_f32_16x16x32_bf16 v[110:113], v[180:183], v[188:191], v[110:113]
	v_mfma_f32_16x16x32_bf16 v[98:101], v[172:175], v[216:219], v[98:101]
	v_mfma_f32_16x16x32_bf16 v[94:97], v[180:183], v[216:219], v[94:97]
	v_mfma_f32_16x16x32_bf16 v[82:85], v[172:175], v[224:227], v[82:85]
	v_mfma_f32_16x16x32_bf16 v[78:81], v[180:183], v[224:227], v[78:81]
	v_mfma_f32_16x16x32_bf16 v[70:73], v[172:175], v[232:235], v[70:73]
	v_mfma_f32_16x16x32_bf16 v[66:69], v[180:183], v[232:235], v[66:69]
	v_mfma_f32_16x16x32_bf16 v[114:117], v[176:179], v[212:215], v[114:117]
	v_mfma_f32_16x16x32_bf16 v[110:113], v[184:187], v[212:215], v[110:113]
	v_mfma_f32_16x16x32_bf16 v[98:101], v[176:179], v[220:223], v[98:101]
	v_mfma_f32_16x16x32_bf16 v[94:97], v[184:187], v[220:223], v[94:97]
	v_mfma_f32_16x16x32_bf16 v[82:85], v[176:179], v[228:231], v[82:85]
	v_mfma_f32_16x16x32_bf16 v[78:81], v[184:187], v[228:231], v[78:81]
	v_mfma_f32_16x16x32_bf16 v[70:73], v[176:179], v[236:239], v[70:73]
	v_mfma_f32_16x16x32_bf16 v[66:69], v[184:187], v[236:239], v[66:69]
	s_barrier
; #define PG8_STAGE(bufoff, gbase, voff) do { _Pragma("unroll") for (int _i = 0; _i < 2; ++_i) \
;         __builtin_amdgcn_global_load_lds((const unsigned*)((const char*)(gbase) + (voff)[_i]), (PG8_LAS unsigned*)(lds + (bufoff) + ldsw + _i * 8192), 16, 0, 0); } while (0)
; #define PG8_LDA(dst, b, h) do { _Pragma("unroll") for (int m = 0; m < 4; ++m) _Pragma("unroll") for (int k = 0; k < 2; ++k) dst[m][k] = *(const PG8_LAS bf16x8*)(lds + PG8_SA(b, h) + aoff + m * 2048 + k * 1024); } while (0)
; #define PG8_MMA(ai, bj, At, Bt) do { __builtin_amdgcn_s_setprio(1); _Pragma("unroll") for (int m = 0; m < 4; ++m) _Pragma("unroll") for (int n = 0; n < 2; ++n) _Pragma("unroll") for (int k = 0; k < 2; ++k) \
;         acc[ai][bj][m][n] = __builtin_amdgcn_mfma_f32_16x16x32_bf16(Bt[n][k], At[m][k], acc[ai][bj][m][n], 0, 0, 0); __builtin_amdgcn_s_setprio(0); } while (0)
; #define PG8_WAIT_V(n) asm volatile("s_waitcnt vmcnt(" #n ")" ::: "memory")
; #define PG8_WAIT_L(n) asm volatile("s_waitcnt lgkmcnt(" #n ")" ::: "memory")
; #define PG8_BAR __builtin_amdgcn_s_barrier()
; #define PG8_SCHED __builtin_amdgcn_sched_barrier(0)
; template <class Epi, class Sched, bool ALIGN_EPI = false, bool SP2 = false>
; __device__ __forceinline__ void gemm_phase(PG8_LAS unsigned char* lds, const Gemm g, const Sched& S, const Epi& E, int wave_in) {
;     ...
;             PG8_LDA(At, 1, 1); PG8_STAGE(PG8_SB(1, 0), b3, voffB); PG8_STAGE(PG8_SB(1, 1), b3 + hstep, voffB); PG8_STAGE(PG8_SA(1, 0), a3, voffA);
;             PG8_WAIT_V(8); PG8_WAIT_L(0); PG8_BAR; PG8_MMA(1, 0, At, B0); PG8_MMA(1, 1, At, B1); PG8_BAR; PG8_SCHED;
	s_add_i32 s26, s47, s30
	v_lshl_add_u64 v[144:145], v[144:145], 0, s[84:85]
	s_mov_b32 m0, s26
	ds_read_b128 v[188:191], v149 offset:49152
	ds_read_b128 v[212:215], v149 offset:50176
	ds_read_b128 v[216:219], v149 offset:51200
	ds_read_b128 v[220:223], v149 offset:52224
	ds_read_b128 v[224:227], v149 offset:53248
	ds_read_b128 v[228:231], v149 offset:54272
	ds_read_b128 v[232:235], v149 offset:55296
	ds_read_b128 v[236:239], v149 offset:56320
	global_load_lds_dwordx4 v[144:145], off
	s_add_i32 m0, s26, 0x2000
	s_add_u32 s24, s24, 0x40080
	v_lshl_add_u64 v[144:145], v[192:193], 0, s[84:85]
	s_addc_u32 s25, s25, 0
	s_add_i32 s26, s48, s30
	global_load_lds_dwordx4 v[144:145], off
	v_lshl_add_u64 v[144:145], s[24:25], 0, v[0:1]
	s_mov_b32 m0, s26
	s_nop 0
	global_load_lds_dwordx4 v[144:145], off
	v_lshl_add_u64 v[144:145], s[24:25], 0, v[130:131]
	s_add_i32 m0, s26, 0x2000
	s_nop 0
	global_load_lds_dwordx4 v[144:145], off
	v_lshl_add_u64 v[144:145], v[240:241], 0, s[84:85]
	s_mov_b32 m0, s37
	s_nop 0
	global_load_lds_dwordx4 v[144:145], off
	v_lshl_add_u64 v[144:145], v[242:243], 0, s[84:85]
	s_mov_b32 m0, s38
	s_nop 0
	global_load_lds_dwordx4 v[144:145], off
	s_waitcnt vmcnt(8)
	s_waitcnt lgkmcnt(0)
	s_barrier
	s_waitcnt lgkmcnt(0)
	v_mfma_f32_16x16x32_bf16 v[62:65], v[140:143], v[188:191], v[62:65]
	v_mfma_f32_16x16x32_bf16 v[58:61], v[154:157], v[188:191], v[58:61]
	v_mfma_f32_16x16x32_bf16 v[54:57], v[140:143], v[216:219], v[54:57]
	v_mfma_f32_16x16x32_bf16 v[42:45], v[154:157], v[216:219], v[42:45]
	v_mfma_f32_16x16x32_bf16 v[38:41], v[140:143], v[224:227], v[38:41]
	v_mfma_f32_16x16x32_bf16 v[26:29], v[154:157], v[224:227], v[26:29]
	v_mfma_f32_16x16x32_bf16 v[22:25], v[140:143], v[232:235], v[22:25]
	v_mfma_f32_16x16x32_bf16 v[10:13], v[154:157], v[232:235], v[10:13]
	v_mfma_f32_16x16x32_bf16 v[62:65], v[150:153], v[212:215], v[62:65]
	v_mfma_f32_16x16x32_bf16 v[58:61], v[168:171], v[212:215], v[58:61]
	v_mfma_f32_16x16x32_bf16 v[54:57], v[150:153], v[220:223], v[54:57]
	v_mfma_f32_16x16x32_bf16 v[42:45], v[168:171], v[220:223], v[42:45]
	v_mfma_f32_16x16x32_bf16 v[38:41], v[150:153], v[228:231], v[38:41]
	v_mfma_f32_16x16x32_bf16 v[26:29], v[168:171], v[228:231], v[26:29]
	v_mfma_f32_16x16x32_bf16 v[22:25], v[150:153], v[236:239], v[22:25]
	v_mfma_f32_16x16x32_bf16 v[10:13], v[168:171], v[236:239], v[10:13]
	v_mfma_f32_16x16x32_bf16 v[50:53], v[172:175], v[188:191], v[50:53]
	v_mfma_f32_16x16x32_bf16 v[46:49], v[180:183], v[188:191], v[46:49]
	v_mfma_f32_16x16x32_bf16 v[34:37], v[172:175], v[216:219], v[34:37]
	v_mfma_f32_16x16x32_bf16 v[30:33], v[180:183], v[216:219], v[30:33]
	v_mfma_f32_16x16x32_bf16 v[18:21], v[172:175], v[224:227], v[18:21]
	v_mfma_f32_16x16x32_bf16 v[14:17], v[180:183], v[224:227], v[14:17]
	v_mfma_f32_16x16x32_bf16 v[6:9], v[172:175], v[232:235], v[6:9]
	v_mfma_f32_16x16x32_bf16 v[2:5], v[180:183], v[232:235], v[2:5]
	v_mfma_f32_16x16x32_bf16 v[50:53], v[176:179], v[212:215], v[50:53]
	v_mfma_f32_16x16x32_bf16 v[46:49], v[184:187], v[212:215], v[46:49]
	v_mfma_f32_16x16x32_bf16 v[34:37], v[176:179], v[220:223], v[34:37]
	v_mfma_f32_16x16x32_bf16 v[30:33], v[184:187], v[220:223], v[30:33]
	v_mfma_f32_16x16x32_bf16 v[18:21], v[176:179], v[228:231], v[18:21]
	v_mfma_f32_16x16x32_bf16 v[14:17], v[184:187], v[228:231], v[14:17]
	v_mfma_f32_16x16x32_bf16 v[6:9], v[176:179], v[236:239], v[6:9]
	v_mfma_f32_16x16x32_bf16 v[2:5], v[184:187], v[236:239], v[2:5]
	s_barrier
	s_add_i32 s46, s46, 2
	s_add_u32 s22, s22, 0x100
	s_addc_u32 s23, s23, 0
	s_add_u32 s44, s44, 0x100
	s_addc_u32 s45, s45, 0
	s_cmp_gt_u32 s46, 13
	s_cbranch_scc0 .LBB0_84
	s_and_b64 vcc, exec, s[8:9]
	v_readlane_b32 s26, v254, 6
	v_readlane_b32 s27, v254, 7
	s_cbranch_vccz .LBB0_87
	s_barrier
